# attention QK: issue all 8 K-fragment ds_reads up front with counted lgkmcnt, reuse 5 fragments for second q-block
# speedup vs baseline: 1.0035x; 1.0035x over previous
; #define LAS __attribute__((address_space(3)))
; __device__ __forceinline__ int crow(int r, int hi) { return (r & 3) + 8 * (r >> 2) + 4 * hi; }
; __device__ __forceinline__ void attn_unit(LAS unsigned char* lds, bf16_t* Y, const bf16_t* KB, const bf16_t* VT, const float* sink, int b, int kvh, int qb, bool isctx) {
;     ...
;                 for (int ks = 0; ks < 4; ++ks) { const bf16x8 kf = *(const LAS bf16x8*)(Ks + ((32 * kb + r32) * 72 + 16 * ks + 8 * hi) * 2);
;                     s[kb] = __builtin_amdgcn_mfma_f32_32x32x16_bf16(kf, qf[j][ks], s[kb], 0, 0, 0); }
;             if (it < ntl) { const int ks0 = qb * 128 - 128 + 64 * it;
; #pragma unroll
;                 for (int kb = 0; kb < 2; ++kb)
; #pragma unroll
;                     for (int r = 0; r < 16; ++r) { const int dk = (tq0 + 32 * j + r32) - (ks0 + 32 * kb + crow(r, hi)); if (dk > 128 || dk < -128) s[kb][r] = -1e30f; } }
.LBB0_254:
	v_add_u32_e32 v64, s67, v142
	v_add_u32_e32 v178, v64, v153
	ds_read_b128 v[64:67], v178
	ds_read_b128 v[68:71], v178 offset:32
	ds_read_b128 v[222:225], v178 offset:64
	ds_read_b128 v[226:229], v178 offset:96
	ds_read_b128 v[230:233], v178 offset:4608
	ds_read_b128 v[234:237], v178 offset:4640
	ds_read_b128 v[246:249], v178 offset:4672
	ds_read_b128 v[174:177], v178 offset:4704
	s_cmp_lt_i32 s66, 6
	s_cselect_b64 s[46:47], -1, 0
	s_cmp_gt_i32 s66, 5
	s_waitcnt lgkmcnt(7)
	v_mfma_f32_32x32x16_bf16 v[80:95], v[64:67], v[96:99], 0
	s_waitcnt lgkmcnt(6)
	v_mfma_f32_32x32x16_bf16 v[80:95], v[68:71], v[100:103], v[80:95]
	s_waitcnt lgkmcnt(5)
	v_mfma_f32_32x32x16_bf16 v[80:95], v[222:225], v[104:107], v[80:95]
	s_waitcnt lgkmcnt(4)
	v_mfma_f32_32x32x16_bf16 v[80:95], v[226:229], v[108:111], v[80:95]
	s_waitcnt lgkmcnt(3)
	v_mfma_f32_32x32x16_bf16 v[64:79], v[230:233], v[96:99], 0
	s_waitcnt lgkmcnt(2)
	v_mfma_f32_32x32x16_bf16 v[64:79], v[234:237], v[100:103], v[64:79]
	s_waitcnt lgkmcnt(1)
	v_mfma_f32_32x32x16_bf16 v[64:79], v[246:249], v[104:107], v[64:79]
	s_waitcnt lgkmcnt(0)
	v_mfma_f32_32x32x16_bf16 v[64:79], v[174:177], v[108:111], v[64:79]
	v_subrev_u32_e32 v175, s63, v169
	s_cbranch_scc1 .LBB0_256
	v_readfirstlane_b32 s98, v242
	s_bfe_u32 s98, s98, 0x10006
	s_sub_i32 s99, s66, s98
	s_add_i32 s99, s99, -1
	s_cmp_lt_u32 s99, 3
	s_cbranch_scc1 .LBB0_256
	v_add_u32_e32 v173, v175, v152
	v_cmp_gt_u32_e32 vcc, s94, v173
	v_add_u32_e32 v173, v175, v154
	s_nop 0
	v_cndmask_b32_e32 v80, v80, v245, vcc
	v_cmp_lt_u32_e32 vcc, s20, v173
	v_add_u32_e32 v173, v175, v155
	s_nop 0
	v_cndmask_b32_e32 v81, v245, v81, vcc
	v_cmp_lt_u32_e32 vcc, s20, v173
	v_add_u32_e32 v173, v175, v156
	s_nop 0
	v_cndmask_b32_e32 v82, v245, v82, vcc
	v_cmp_lt_u32_e32 vcc, s20, v173
	v_add_u32_e32 v173, v175, v157
	s_nop 0
	v_cndmask_b32_e32 v83, v245, v83, vcc
	v_cmp_lt_u32_e32 vcc, s20, v173
	v_add_u32_e32 v173, v175, v158
	s_nop 0
	v_cndmask_b32_e32 v84, v245, v84, vcc
	v_cmp_lt_u32_e32 vcc, s20, v173
	v_add_u32_e32 v173, v175, v159
	s_nop 0
	v_cndmask_b32_e32 v85, v245, v85, vcc
	v_cmp_lt_u32_e32 vcc, s20, v173
	v_add_u32_e32 v173, v175, v160
	s_nop 0
	v_cndmask_b32_e32 v86, v245, v86, vcc
	v_cmp_lt_u32_e32 vcc, s20, v173
	v_add_u32_e32 v173, v175, v161
	s_nop 0
	v_cndmask_b32_e32 v87, v245, v87, vcc
	v_cmp_lt_u32_e32 vcc, s20, v173
	v_add_u32_e32 v173, v175, v162
	s_nop 0
	v_cndmask_b32_e32 v88, v245, v88, vcc
	v_cmp_lt_u32_e32 vcc, s20, v173
	v_add_u32_e32 v173, v175, v163
	s_nop 0
	v_cndmask_b32_e32 v89, v245, v89, vcc
	v_cmp_lt_u32_e32 vcc, s20, v173
	v_add_u32_e32 v173, v175, v164
	s_nop 0
	v_cndmask_b32_e32 v90, v245, v90, vcc
	v_cmp_lt_u32_e32 vcc, s20, v173
	v_add_u32_e32 v173, v175, v165
	s_nop 0
	v_cndmask_b32_e32 v91, v245, v91, vcc
	v_cmp_lt_u32_e32 vcc, s20, v173
	v_add_u32_e32 v173, v175, v166
	s_nop 0
	v_cndmask_b32_e32 v92, v245, v92, vcc
	v_cmp_lt_u32_e32 vcc, s20, v173
	v_add_u32_e32 v173, v175, v167
	s_nop 0
	v_cndmask_b32_e32 v93, v245, v93, vcc
	v_cmp_lt_u32_e32 vcc, s20, v173
	v_add_u32_e32 v173, v175, v168
	s_nop 0
	v_cndmask_b32_e32 v94, v245, v94, vcc
	v_cmp_lt_u32_e32 vcc, s20, v173
	v_subrev_u32_e32 v173, s63, v170
	v_add_u32_e32 v174, v173, v152
	v_cndmask_b32_e32 v95, v245, v95, vcc
	v_cmp_lt_u32_e32 vcc, s20, v174
	v_add_u32_e32 v174, v173, v154
	s_nop 0
	v_cndmask_b32_e32 v64, v245, v64, vcc
	v_cmp_lt_u32_e32 vcc, s20, v174
	v_add_u32_e32 v174, v173, v155
	s_nop 0
	v_cndmask_b32_e32 v65, v245, v65, vcc
	v_cmp_lt_u32_e32 vcc, s20, v174
	v_add_u32_e32 v174, v173, v156
	s_nop 0
	v_cndmask_b32_e32 v66, v245, v66, vcc
	v_cmp_lt_u32_e32 vcc, s20, v174
	v_add_u32_e32 v174, v173, v157
	s_nop 0
	v_cndmask_b32_e32 v67, v245, v67, vcc
	v_cmp_lt_u32_e32 vcc, s20, v174
	v_add_u32_e32 v174, v173, v158
	s_nop 0
	v_cndmask_b32_e32 v68, v245, v68, vcc
	v_cmp_lt_u32_e32 vcc, s20, v174
	v_add_u32_e32 v174, v173, v159
	s_nop 0
	v_cndmask_b32_e32 v69, v245, v69, vcc
	v_cmp_lt_u32_e32 vcc, s20, v174
	v_add_u32_e32 v174, v173, v160
	s_nop 0
	v_cndmask_b32_e32 v70, v245, v70, vcc
	v_cmp_lt_u32_e32 vcc, s20, v174
	v_add_u32_e32 v174, v173, v161
	s_nop 0
	v_cndmask_b32_e32 v71, v245, v71, vcc
	v_cmp_lt_u32_e32 vcc, s20, v174
	v_add_u32_e32 v174, v173, v162
	s_nop 0
	v_cndmask_b32_e32 v72, v245, v72, vcc
	v_cmp_lt_u32_e32 vcc, s20, v174
	v_add_u32_e32 v174, v173, v163
	s_nop 0
	v_cndmask_b32_e32 v73, v245, v73, vcc
	v_cmp_lt_u32_e32 vcc, s20, v174
	v_add_u32_e32 v174, v173, v164
	s_nop 0
	v_cndmask_b32_e32 v74, v245, v74, vcc
	v_cmp_lt_u32_e32 vcc, s20, v174
	v_add_u32_e32 v174, v173, v165
	s_nop 0
	v_cndmask_b32_e32 v75, v245, v75, vcc
	v_cmp_lt_u32_e32 vcc, s20, v174
	v_add_u32_e32 v174, v173, v166
	s_nop 0
	v_cndmask_b32_e32 v76, v245, v76, vcc
	v_cmp_lt_u32_e32 vcc, s20, v174
	v_add_u32_e32 v174, v173, v167
	v_add_u32_e32 v173, v173, v168
	v_cndmask_b32_e32 v77, v245, v77, vcc
	v_cmp_lt_u32_e32 vcc, s20, v174
	s_nop 1
	v_cndmask_b32_e32 v78, v245, v78, vcc
	v_cmp_lt_u32_e32 vcc, s20, v173
	s_nop 1
	v_cndmask_b32_e32 v79, v245, v79, vcc
; __device__ __forceinline__ unsigned cvt_pk_bf16(float lo, float hi) { unsigned r; asm volatile("v_cvt_pk_bf16_f32 %0, %1, %2" : "=v"(r) : "v"(lo), "v"(hi)); return r; }
; __device__ __forceinline__ void attn_unit(LAS unsigned char* lds, bf16_t* Y, const bf16_t* KB, const bf16_t* VT, const float* sink, int b, int kvh, int qb, bool isctx) {
;     ...
;                 for (int ks = 0; ks < 4; ++ks) { const bf16x8 kf = *(const LAS bf16x8*)(Ks + ((32 * kb + r32) * 72 + 16 * ks + 8 * hi) * 2);
;                     s[kb] = __builtin_amdgcn_mfma_f32_32x32x16_bf16(kf, qf[j][ks], s[kb], 0, 0, 0); }
;     ...
;             float mx = s[0][0];
; #pragma unroll
;             for (int kb = 0; kb < 2; ++kb)
; #pragma unroll
;                 for (int r = 0; r < 16; ++r) mx = fmaxf(mx, s[kb][r]);
;             mx = fmaxf(mx, __shfl_xor(mx, 32));
;             const float mnew = fmaxf(mx_[j], mx), alpha = __builtin_amdgcn_exp2f(mx_[j] - mnew); mx_[j] = mnew;
;             float ls = 0.f;
; #pragma unroll
;             for (int kb = 0; kb < 2; ++kb)
; #pragma unroll
;                 for (int r = 0; r < 16; ++r) { const float pv = __builtin_amdgcn_exp2f(s[kb][r] - mnew); s[kb][r] = pv; ls += pv; }
;             l_[j] = l_[j] * alpha + ls;
; #pragma unroll
;             for (int d = 0; d < 2; ++d)
; #pragma unroll
;                 for (int r = 0; r < 16; ++r) o[j][d][r] *= alpha;
; #pragma unroll
;             for (int kk = 0; kk < 4; ++kk) { const int kb = kk >> 1, jj = kk & 1; u32x4 w;
;                 w.x = cvt_pk_bf16(s[kb][8 * jj + 0], s[kb][8 * jj + 1]); w.y = cvt_pk_bf16(s[kb][8 * jj + 2], s[kb][8 * jj + 3]);
;                 w.z = cvt_pk_bf16(s[kb][8 * jj + 4], s[kb][8 * jj + 5]); w.w = cvt_pk_bf16(s[kb][8 * jj + 6], s[kb][8 * jj + 7]);
;                 pf[kk] = __builtin_bit_cast(bf16x8, w); }
; #pragma unroll
;             for (int d = 0; d < 2; ++d)
; #pragma unroll
;                 for (int kk = 0; kk < 4; ++kk) { const int kb = kk >> 1, jj = kk & 1;
;                     const LAS unsigned char* vp = Vs + ((32 * d + r32) * 72 + 32 * kb + 16 * jj + 4 * hi) * 2;
;                     const u32x2 lo = *(const LAS u32x2*)vp, hh = *(const LAS u32x2*)(vp + 16);
;                     const u32x4 w = {lo.x, lo.y, hh.x, hh.y}; const bf16x8 vf = __builtin_bit_cast(bf16x8, w);
;                     o[j][d] = __builtin_amdgcn_mfma_f32_32x32x16_bf16(vf, pf[kk], o[j][d], 0, 0, 0); }
.LBB0_256:
	v_max_f32_e32 v173, v81, v81
	v_max_f32_e32 v174, v80, v80
	v_max_f32_e32 v173, v174, v173
	v_max3_f32 v173, v173, v82, v83
	v_max3_f32 v173, v173, v84, v85
	v_max3_f32 v173, v173, v86, v87
	v_max3_f32 v173, v173, v88, v89
	v_max3_f32 v173, v173, v90, v91
	v_max3_f32 v173, v173, v92, v93
	v_max3_f32 v173, v173, v94, v95
	v_max3_f32 v173, v173, v64, v65
	v_max3_f32 v173, v173, v66, v67
	v_max3_f32 v173, v173, v68, v69
	v_max3_f32 v173, v173, v70, v71
	v_max3_f32 v173, v173, v72, v73
	v_max3_f32 v173, v173, v74, v75
	v_max3_f32 v173, v173, v76, v77
	v_max3_f32 v173, v173, v78, v79
	ds_bpermute_b32 v174, v149, v173
	v_add_u32_e32 v176, s67, v140
	s_andn2_b64 vcc, exec, s[46:47]
	s_waitcnt lgkmcnt(0)
	v_max3_f32 v173, v148, v173, v174
	v_sub_f32_e32 v80, v80, v173
	v_sub_f32_e32 v64, v64, v173
	v_exp_f32_e32 v179, v80
	v_sub_f32_e32 v80, v81, v173
	v_exp_f32_e32 v199, v64
	v_sub_f32_e32 v64, v65, v173
	v_exp_f32_e32 v181, v80
	v_sub_f32_e32 v80, v82, v173
	v_exp_f32_e32 v200, v64
	v_sub_f32_e32 v64, v66, v173
	v_exp_f32_e32 v183, v80
	v_sub_f32_e32 v80, v83, v173
	v_exp_f32_e32 v201, v64
	v_sub_f32_e32 v64, v67, v173
	v_exp_f32_e32 v185, v80
	v_sub_f32_e32 v80, v84, v173
	v_exp_f32_e32 v202, v64
	v_sub_f32_e32 v64, v68, v173
	v_exp_f32_e32 v187, v80
	v_sub_f32_e32 v80, v85, v173
	v_exp_f32_e32 v203, v64
	v_sub_f32_e32 v64, v69, v173
	v_exp_f32_e32 v188, v80
	v_sub_f32_e32 v80, v86, v173
	v_exp_f32_e32 v204, v64
	v_sub_f32_e32 v64, v70, v173
	v_exp_f32_e32 v189, v80
	v_sub_f32_e32 v80, v87, v173
	v_exp_f32_e32 v205, v64
	v_sub_f32_e32 v64, v71, v173
	v_exp_f32_e32 v190, v80
	v_sub_f32_e32 v80, v88, v173
	v_exp_f32_e32 v206, v64
	v_sub_f32_e32 v64, v72, v173
	v_exp_f32_e32 v191, v80
	v_sub_f32_e32 v80, v89, v173
	v_exp_f32_e32 v207, v64
	v_sub_f32_e32 v64, v73, v173
	v_exp_f32_e32 v192, v80
	v_sub_f32_e32 v80, v90, v173
	v_exp_f32_e32 v212, v64
	v_sub_f32_e32 v64, v74, v173
	v_exp_f32_e32 v193, v80
	v_sub_f32_e32 v80, v91, v173
	v_exp_f32_e32 v213, v64
	v_sub_f32_e32 v64, v75, v173
	v_exp_f32_e32 v194, v80
	v_sub_f32_e32 v80, v92, v173
	v_exp_f32_e32 v180, v64
	v_sub_f32_e32 v64, v76, v173
	v_exp_f32_e32 v195, v80
	v_sub_f32_e32 v80, v93, v173
	v_exp_f32_e32 v182, v64
	v_sub_f32_e32 v64, v77, v173
	v_sub_f32_e32 v148, v148, v173
	v_exp_f32_e32 v196, v80
	v_sub_f32_e32 v80, v94, v173
	v_exp_f32_e32 v184, v64
	v_sub_f32_e32 v64, v78, v173
	v_add_u32_e32 v88, v176, v153
	v_exp_f32_e32 v197, v80
	v_sub_f32_e32 v80, v95, v173
	v_exp_f32_e32 v186, v64
	v_sub_f32_e32 v64, v79, v173
	v_exp_f32_e32 v148, v148
	v_add_u32_e32 v176, 0x2000, v88
	v_exp_f32_e32 v198, v80
	v_exp_f32_e32 v174, v64
	v_cvt_pk_bf16_f32 v64, v179, v181
	v_cvt_pk_bf16_f32 v65, v183, v185
	v_cvt_pk_bf16_f32 v66, v187, v188
	v_cvt_pk_bf16_f32 v67, v189, v190
	v_cvt_pk_bf16_f32 v68, v191, v192
	v_cvt_pk_bf16_f32 v69, v193, v194
	v_cvt_pk_bf16_f32 v70, v195, v196
	v_cvt_pk_bf16_f32 v71, v197, v198
	v_cvt_pk_bf16_f32 v72, v199, v200
	v_cvt_pk_bf16_f32 v73, v201, v202
	v_cvt_pk_bf16_f32 v74, v203, v204
	v_cvt_pk_bf16_f32 v75, v205, v206
	v_cvt_pk_bf16_f32 v76, v207, v212
	v_cvt_pk_bf16_f32 v77, v213, v180
	v_cvt_pk_bf16_f32 v78, v182, v184
	v_cvt_pk_bf16_f32 v79, v186, v174
	ds_read2_b64 v[80:83], v176 offset0:128 offset1:130
	ds_read2_b64 v[84:87], v176 offset0:132 offset1:134
	v_pk_mul_f32 v[62:63], v[62:63], v[148:149] op_sel_hi:[1,0]
	v_pk_mul_f32 v[60:61], v[60:61], v[148:149] op_sel_hi:[1,0]
	v_pk_mul_f32 v[58:59], v[58:59], v[148:149] op_sel_hi:[1,0]
	v_pk_mul_f32 v[56:57], v[56:57], v[148:149] op_sel_hi:[1,0]
	v_pk_mul_f32 v[54:55], v[54:55], v[148:149] op_sel_hi:[1,0]
	v_pk_mul_f32 v[52:53], v[52:53], v[148:149] op_sel_hi:[1,0]
	v_pk_mul_f32 v[50:51], v[50:51], v[148:149] op_sel_hi:[1,0]
	v_pk_mul_f32 v[48:49], v[48:49], v[148:149] op_sel_hi:[1,0]
	v_add_u32_e32 v177, 0x3000, v88
	v_pk_mul_f32 v[46:47], v[46:47], v[148:149] op_sel_hi:[1,0]
	s_waitcnt lgkmcnt(1)
	v_mfma_f32_32x32x16_bf16 v[48:63], v[80:83], v[64:67], v[48:63]
	ds_read2_b64 v[80:83], v176 offset0:136 offset1:138
	v_mul_f32_e64 v44, v44, v148
	v_mul_f32_e64 v45, v45, v148
	v_mul_f32_e64 v42, v42, v148
	v_mul_f32_e64 v43, v43, v148
	v_pk_mul_f32 v[40:41], v[40:41], v[148:149] op_sel_hi:[1,0]
	v_pk_mul_f32 v[38:39], v[38:39], v[148:149] op_sel_hi:[1,0]
	v_pk_mul_f32 v[36:37], v[36:37], v[148:149] op_sel_hi:[1,0]
	v_pk_mul_f32 v[34:35], v[34:35], v[148:149] op_sel_hi:[1,0]
	s_waitcnt lgkmcnt(1)
	v_mfma_f32_32x32x16_bf16 v[48:63], v[84:87], v[68:71], v[48:63]
	v_mul_f32_e64 v32, v32, v148
	v_mul_f32_e64 v33, v33, v148
	s_waitcnt lgkmcnt(0)
	v_mfma_f32_32x32x16_bf16 v[48:63], v[80:83], v[72:75], v[48:63]
	ds_read2_b64 v[80:83], v176 offset0:140 offset1:142
	s_waitcnt lgkmcnt(0)
	v_mfma_f32_32x32x16_bf16 v[48:63], v[80:83], v[76:79], v[48:63]
	ds_read2_b64 v[80:83], v177 offset0:192 offset1:194
	s_waitcnt lgkmcnt(0)
	v_mfma_f32_32x32x16_bf16 v[32:47], v[80:83], v[64:67], v[32:47]
	ds_read2_b64 v[64:67], v177 offset0:196 offset1:198
	s_waitcnt lgkmcnt(0)
	v_mfma_f32_32x32x16_bf16 v[32:47], v[64:67], v[68:71], v[32:47]
	ds_read2_b64 v[64:67], v177 offset0:200 offset1:202
	s_waitcnt lgkmcnt(0)
	v_mfma_f32_32x32x16_bf16 v[32:47], v[64:67], v[72:75], v[32:47]
	ds_read2_b64 v[64:67], v177 offset0:204 offset1:206
	s_waitcnt lgkmcnt(0)
	v_mfma_f32_32x32x16_bf16 v[32:47], v[64:67], v[76:79], v[32:47]
	ds_read_b128 v[64:67], v178
	ds_read_b128 v[68:71], v178 offset:32
	ds_read_b128 v[218:221], v178 offset:4704
	s_waitcnt lgkmcnt(2)
	v_mfma_f32_32x32x16_bf16 v[80:95], v[64:67], v[112:115], 0
	s_waitcnt lgkmcnt(1)
	v_mfma_f32_32x32x16_bf16 v[80:95], v[68:71], v[116:119], v[80:95]
	v_mfma_f32_32x32x16_bf16 v[80:95], v[222:225], v[120:123], v[80:95]
	v_mfma_f32_32x32x16_bf16 v[80:95], v[226:229], v[124:127], v[80:95]
	v_mfma_f32_32x32x16_bf16 v[64:79], v[230:233], v[112:115], 0
	v_mfma_f32_32x32x16_bf16 v[64:79], v[234:237], v[116:119], v[64:79]
	v_mfma_f32_32x32x16_bf16 v[64:79], v[246:249], v[120:123], v[64:79]
	s_waitcnt lgkmcnt(0)
	v_mfma_f32_32x32x16_bf16 v[64:79], v[218:221], v[124:127], v[64:79]
	s_cbranch_vccnz .LBB0_258
; __device__ __forceinline__ int crow(int r, int hi) { return (r & 3) + 8 * (r >> 2) + 4 * hi; }
; __device__ __forceinline__ void attn_unit(LAS unsigned char* lds, bf16_t* Y, const bf16_t* KB, const bf16_t* VT, const float* sink, int b, int kvh, int qb, bool isctx) {
;     ...
;             if (it < ntl) { const int ks0 = qb * 128 - 128 + 64 * it;
; #pragma unroll
;                 for (int kb = 0; kb < 2; ++kb)
; #pragma unroll
;                     for (int r = 0; r < 16; ++r) { const int dk = (tq0 + 32 * j + r32) - (ks0 + 32 * kb + crow(r, hi)); if (dk > 128 || dk < -128) s[kb][r] = -1e30f; } }
	v_readfirstlane_b32 s98, v242
	s_bfe_u32 s98, s98, 0x10006
	s_sub_i32 s99, s66, s98
	s_add_i32 s99, s99, -1
	s_cmp_lt_u32 s99, 3
	s_cbranch_scc1 .LBB0_258
	v_subrev_u32_e32 v178, s63, v171
	v_add_u32_e32 v210, v178, v152
	v_cmp_gt_u32_e32 vcc, s94, v210
	v_add_u32_e32 v210, v178, v154
	s_nop 0
	v_cndmask_b32_e32 v80, v80, v245, vcc
	v_cmp_lt_u32_e32 vcc, s20, v210
	v_add_u32_e32 v210, v178, v155
	s_nop 0
	v_cndmask_b32_e32 v81, v245, v81, vcc
	v_cmp_lt_u32_e32 vcc, s20, v210
	v_add_u32_e32 v210, v178, v156
	s_nop 0
	v_cndmask_b32_e32 v82, v245, v82, vcc
	v_cmp_lt_u32_e32 vcc, s20, v210
	v_add_u32_e32 v210, v178, v157
	s_nop 0
	v_cndmask_b32_e32 v83, v245, v83, vcc
	v_cmp_lt_u32_e32 vcc, s20, v210
	v_add_u32_e32 v210, v178, v158
	s_nop 0
	v_cndmask_b32_e32 v84, v245, v84, vcc
	v_cmp_lt_u32_e32 vcc, s20, v210
	v_add_u32_e32 v210, v178, v159
	s_nop 0
	v_cndmask_b32_e32 v85, v245, v85, vcc
	v_cmp_lt_u32_e32 vcc, s20, v210
	v_add_u32_e32 v210, v178, v160
	s_nop 0
	v_cndmask_b32_e32 v86, v245, v86, vcc
	v_cmp_lt_u32_e32 vcc, s20, v210
	v_add_u32_e32 v210, v178, v161
	s_nop 0
	v_cndmask_b32_e32 v87, v245, v87, vcc
	v_cmp_lt_u32_e32 vcc, s20, v210
	v_add_u32_e32 v210, v178, v162
	s_nop 0
	v_cndmask_b32_e32 v88, v245, v88, vcc
	v_cmp_lt_u32_e32 vcc, s20, v210
	v_add_u32_e32 v210, v178, v163
	s_nop 0
	v_cndmask_b32_e32 v89, v245, v89, vcc
	v_cmp_lt_u32_e32 vcc, s20, v210
	v_add_u32_e32 v210, v178, v164
	s_nop 0
	v_cndmask_b32_e32 v90, v245, v90, vcc
	v_cmp_lt_u32_e32 vcc, s20, v210
	v_add_u32_e32 v210, v178, v165
	s_nop 0
	v_cndmask_b32_e32 v91, v245, v91, vcc
	v_cmp_lt_u32_e32 vcc, s20, v210
	v_add_u32_e32 v210, v178, v166
	s_nop 0
	v_cndmask_b32_e32 v92, v245, v92, vcc
	v_cmp_lt_u32_e32 vcc, s20, v210
	v_add_u32_e32 v210, v178, v167
	v_add_u32_e32 v178, v178, v168
	v_cndmask_b32_e32 v93, v245, v93, vcc
	v_cmp_lt_u32_e32 vcc, s20, v210
	s_nop 1
	v_cndmask_b32_e32 v94, v245, v94, vcc
	v_cmp_lt_u32_e32 vcc, s20, v178
	v_add_u32_e32 v178, v175, v152
	s_nop 0
	v_cndmask_b32_e32 v95, v245, v95, vcc
	v_cmp_lt_u32_e32 vcc, s20, v178
	v_add_u32_e32 v178, v175, v154
	s_nop 0
	v_cndmask_b32_e32 v64, v245, v64, vcc
	v_cmp_lt_u32_e32 vcc, s20, v178
	v_add_u32_e32 v178, v175, v155
	s_nop 0
	v_cndmask_b32_e32 v65, v245, v65, vcc
	v_cmp_lt_u32_e32 vcc, s20, v178
	v_add_u32_e32 v178, v175, v156
	s_nop 0
	v_cndmask_b32_e32 v66, v245, v66, vcc
	v_cmp_lt_u32_e32 vcc, s20, v178
	v_add_u32_e32 v178, v175, v157
	s_nop 0
	v_cndmask_b32_e32 v67, v245, v67, vcc
	v_cmp_lt_u32_e32 vcc, s20, v178
	v_add_u32_e32 v178, v175, v158
	s_nop 0
	v_cndmask_b32_e32 v68, v245, v68, vcc
	v_cmp_lt_u32_e32 vcc, s20, v178
	v_add_u32_e32 v178, v175, v159
	s_nop 0
	v_cndmask_b32_e32 v69, v245, v69, vcc
	v_cmp_lt_u32_e32 vcc, s20, v178
	v_add_u32_e32 v178, v175, v160
	s_nop 0
	v_cndmask_b32_e32 v70, v245, v70, vcc
	v_cmp_lt_u32_e32 vcc, s20, v178
	v_add_u32_e32 v178, v175, v161
	s_nop 0
	v_cndmask_b32_e32 v71, v245, v71, vcc
	v_cmp_lt_u32_e32 vcc, s20, v178
	v_add_u32_e32 v178, v175, v162
	s_nop 0
	v_cndmask_b32_e32 v72, v245, v72, vcc
	v_cmp_lt_u32_e32 vcc, s20, v178
	v_add_u32_e32 v178, v175, v163
	s_nop 0
	v_cndmask_b32_e32 v73, v245, v73, vcc
	v_cmp_lt_u32_e32 vcc, s20, v178
	v_add_u32_e32 v178, v175, v164
	s_nop 0
	v_cndmask_b32_e32 v74, v245, v74, vcc
	v_cmp_lt_u32_e32 vcc, s20, v178
	v_add_u32_e32 v178, v175, v165
	s_nop 0
	v_cndmask_b32_e32 v75, v245, v75, vcc
	v_cmp_lt_u32_e32 vcc, s20, v178
	v_add_u32_e32 v178, v175, v166
	s_nop 0
	v_cndmask_b32_e32 v76, v245, v76, vcc
	v_cmp_lt_u32_e32 vcc, s20, v178
	v_add_u32_e32 v178, v175, v167
	v_add_u32_e32 v175, v175, v168
	v_cndmask_b32_e32 v77, v245, v77, vcc
	v_cmp_lt_u32_e32 vcc, s20, v178
	s_nop 1
	v_cndmask_b32_e32 v78, v245, v78, vcc
	v_cmp_lt_u32_e32 vcc, s20, v175
	s_nop 1
	v_cndmask_b32_e32 v79, v245, v79, vcc
